# attention: nt on Q and gate loads, sc1 on epilogue stores (keep K/V tiles in L2)
# baseline (speedup 1.0000x reference)
.LBB0_687:
	s_or_b64 exec, exec, s[8:9]
	s_add_i32 s10, s10, 1
	s_add_i32 s13, s13, 32
	s_add_i32 s12, s12, 1
	s_add_i32 s11, s11, 1
	ds_read_b128 v[0:3], v170
	s_waitcnt lgkmcnt(0)
	v_mul_f32_e32 v82, v82, v0
	v_mul_f32_e32 v66, v66, v0
	v_mul_f32_e32 v50, v50, v0
	v_mul_f32_e32 v34, v34, v0
	v_mul_f32_e32 v83, v83, v1
	v_mul_f32_e32 v67, v67, v1
	v_mul_f32_e32 v51, v51, v1
	v_mul_f32_e32 v35, v35, v1
	v_mul_f32_e32 v84, v84, v2
	v_mul_f32_e32 v68, v68, v2
	v_mul_f32_e32 v52, v52, v2
	v_mul_f32_e32 v36, v36, v2
	v_mul_f32_e32 v85, v85, v3
	v_mul_f32_e32 v69, v69, v3
	v_mul_f32_e32 v53, v53, v3
	v_mul_f32_e32 v37, v37, v3
	ds_write_b32 v24, v82
	ds_write_b32 v24, v66 offset:128
	ds_write_b32 v24, v50 offset:256
	ds_write_b32 v24, v34 offset:384
	ds_write_b32 v24, v83 offset:528
	ds_write_b32 v24, v67 offset:656
	ds_write_b32 v24, v51 offset:784
	ds_write_b32 v24, v35 offset:912
	ds_write_b32 v24, v84 offset:1056
	ds_write_b32 v24, v68 offset:1184
	ds_write_b32 v24, v52 offset:1312
	ds_write_b32 v24, v36 offset:1440
	ds_write_b32 v24, v85 offset:1584
	ds_write_b32 v24, v69 offset:1712
	ds_write_b32 v24, v53 offset:1840
	ds_write_b32 v24, v37 offset:1968
	s_waitcnt lgkmcnt(0)
	ds_read_b128 v[8:11], v25
	ds_read_b128 v[12:15], v25 offset:16
	ds_read_b128 v[16:19], v25 offset:2112
	ds_read_b128 v[20:23], v25 offset:2128
	s_waitcnt vmcnt(6)
	v_lshlrev_b32_e32 v234, 16, v98
	v_and_b32_e32 v235, 0xffff0000, v98
	v_lshlrev_b32_e32 v236, 16, v99
	v_and_b32_e32 v237, 0xffff0000, v99
	v_lshlrev_b32_e32 v238, 16, v100
	v_and_b32_e32 v239, 0xffff0000, v100
	v_lshlrev_b32_e32 v240, 16, v101
	v_and_b32_e32 v241, 0xffff0000, v101
	s_waitcnt lgkmcnt(2)
	v_mul_f32_e32 v234, v8, v234
	v_mul_f32_e32 v235, v9, v235
	v_mul_f32_e32 v236, v10, v236
	v_mul_f32_e32 v237, v11, v237
	v_mul_f32_e32 v238, v12, v238
	v_mul_f32_e32 v239, v13, v239
	v_mul_f32_e32 v240, v14, v240
	v_mul_f32_e32 v241, v15, v241
	v_cvt_pk_bf16_f32 v28, v234, v235
	v_cvt_pk_bf16_f32 v29, v236, v237
	v_cvt_pk_bf16_f32 v30, v238, v239
	v_cvt_pk_bf16_f32 v31, v240, v241
	global_store_dwordx4 v26, v[28:31], s[50:51] sc1
	v_add_u32_e32 v27, 0x4000, v26
	v_lshlrev_b32_e32 v234, 16, v102
	v_and_b32_e32 v235, 0xffff0000, v102
	v_lshlrev_b32_e32 v236, 16, v103
	v_and_b32_e32 v237, 0xffff0000, v103
	v_lshlrev_b32_e32 v238, 16, v104
	v_and_b32_e32 v239, 0xffff0000, v104
	v_lshlrev_b32_e32 v240, 16, v105
	v_and_b32_e32 v241, 0xffff0000, v105
	s_waitcnt lgkmcnt(0)
	v_mul_f32_e32 v234, v16, v234
	v_mul_f32_e32 v235, v17, v235
	v_mul_f32_e32 v236, v18, v236
	v_mul_f32_e32 v237, v19, v237
	v_mul_f32_e32 v238, v20, v238
	v_mul_f32_e32 v239, v21, v239
	v_mul_f32_e32 v240, v22, v240
	v_mul_f32_e32 v241, v23, v241
	v_cvt_pk_bf16_f32 v242, v234, v235
	v_cvt_pk_bf16_f32 v243, v236, v237
	v_cvt_pk_bf16_f32 v244, v238, v239
	v_cvt_pk_bf16_f32 v245, v240, v241
	global_store_dwordx4 v27, v[242:245], s[50:51] sc1
	v_add_u32_e32 v26, 0x4000, v27
	ds_read_b128 v[0:3], v170 offset:32
	s_waitcnt lgkmcnt(0)
	v_mul_f32_e32 v86, v86, v0
	v_mul_f32_e32 v70, v70, v0
	v_mul_f32_e32 v54, v54, v0
	v_mul_f32_e32 v38, v38, v0
	v_mul_f32_e32 v87, v87, v1
	v_mul_f32_e32 v71, v71, v1
	v_mul_f32_e32 v55, v55, v1
	v_mul_f32_e32 v39, v39, v1
	v_mul_f32_e32 v88, v88, v2
	v_mul_f32_e32 v72, v72, v2
	v_mul_f32_e32 v56, v56, v2
	v_mul_f32_e32 v40, v40, v2
	v_mul_f32_e32 v89, v89, v3
	v_mul_f32_e32 v73, v73, v3
	v_mul_f32_e32 v57, v57, v3
	v_mul_f32_e32 v41, v41, v3
	ds_write_b32 v24, v86
	ds_write_b32 v24, v70 offset:128
	ds_write_b32 v24, v54 offset:256
	ds_write_b32 v24, v38 offset:384
	ds_write_b32 v24, v87 offset:528
	ds_write_b32 v24, v71 offset:656
	ds_write_b32 v24, v55 offset:784
	ds_write_b32 v24, v39 offset:912
	ds_write_b32 v24, v88 offset:1056
	ds_write_b32 v24, v72 offset:1184
	ds_write_b32 v24, v56 offset:1312
	ds_write_b32 v24, v40 offset:1440
	ds_write_b32 v24, v89 offset:1584
	ds_write_b32 v24, v73 offset:1712
	ds_write_b32 v24, v57 offset:1840
	ds_write_b32 v24, v41 offset:1968
	s_waitcnt lgkmcnt(0)
	ds_read_b128 v[8:11], v25
	ds_read_b128 v[12:15], v25 offset:16
	ds_read_b128 v[16:19], v25 offset:2112
	ds_read_b128 v[20:23], v25 offset:2128
	s_waitcnt vmcnt(6)
	v_lshlrev_b32_e32 v234, 16, v106
	v_and_b32_e32 v235, 0xffff0000, v106
	v_lshlrev_b32_e32 v236, 16, v107
	v_and_b32_e32 v237, 0xffff0000, v107
	v_lshlrev_b32_e32 v238, 16, v108
	v_and_b32_e32 v239, 0xffff0000, v108
	v_lshlrev_b32_e32 v240, 16, v109
	v_and_b32_e32 v241, 0xffff0000, v109
	s_waitcnt lgkmcnt(2)
	v_mul_f32_e32 v234, v8, v234
	v_mul_f32_e32 v235, v9, v235
	v_mul_f32_e32 v236, v10, v236
	v_mul_f32_e32 v237, v11, v237
	v_mul_f32_e32 v238, v12, v238
	v_mul_f32_e32 v239, v13, v239
	v_mul_f32_e32 v240, v14, v240
	v_mul_f32_e32 v241, v15, v241
	v_cvt_pk_bf16_f32 v28, v234, v235
	v_cvt_pk_bf16_f32 v29, v236, v237
	v_cvt_pk_bf16_f32 v30, v238, v239
	v_cvt_pk_bf16_f32 v31, v240, v241
	global_store_dwordx4 v26, v[28:31], s[50:51] sc1
	v_add_u32_e32 v27, 0x4000, v26
	v_lshlrev_b32_e32 v234, 16, v110
	v_and_b32_e32 v235, 0xffff0000, v110
	v_lshlrev_b32_e32 v236, 16, v111
	v_and_b32_e32 v237, 0xffff0000, v111
	v_lshlrev_b32_e32 v238, 16, v112
	v_and_b32_e32 v239, 0xffff0000, v112
	v_lshlrev_b32_e32 v240, 16, v113
	v_and_b32_e32 v241, 0xffff0000, v113
	s_waitcnt lgkmcnt(0)
	v_mul_f32_e32 v234, v16, v234
	v_mul_f32_e32 v235, v17, v235
	v_mul_f32_e32 v236, v18, v236
	v_mul_f32_e32 v237, v19, v237
	v_mul_f32_e32 v238, v20, v238
	v_mul_f32_e32 v239, v21, v239
	v_mul_f32_e32 v240, v22, v240
	v_mul_f32_e32 v241, v23, v241
	v_cvt_pk_bf16_f32 v242, v234, v235
	v_cvt_pk_bf16_f32 v243, v236, v237
	v_cvt_pk_bf16_f32 v244, v238, v239
	v_cvt_pk_bf16_f32 v245, v240, v241
	global_store_dwordx4 v27, v[242:245], s[50:51] sc1
	v_add_u32_e32 v26, 0x4000, v27
	ds_read_b128 v[0:3], v170 offset:64
	s_waitcnt lgkmcnt(0)
	v_mul_f32_e32 v90, v90, v0
	v_mul_f32_e32 v74, v74, v0
	v_mul_f32_e32 v58, v58, v0
	v_mul_f32_e32 v42, v42, v0
	v_mul_f32_e32 v91, v91, v1
	v_mul_f32_e32 v75, v75, v1
	v_mul_f32_e32 v59, v59, v1
	v_mul_f32_e32 v43, v43, v1
	v_mul_f32_e32 v92, v92, v2
	v_mul_f32_e32 v76, v76, v2
	v_mul_f32_e32 v60, v60, v2
	v_mul_f32_e32 v44, v44, v2
	v_mul_f32_e32 v93, v93, v3
	v_mul_f32_e32 v77, v77, v3
	v_mul_f32_e32 v61, v61, v3
	v_mul_f32_e32 v45, v45, v3
	ds_write_b32 v24, v90
	ds_write_b32 v24, v74 offset:128
	ds_write_b32 v24, v58 offset:256
	ds_write_b32 v24, v42 offset:384
	ds_write_b32 v24, v91 offset:528
	ds_write_b32 v24, v75 offset:656
	ds_write_b32 v24, v59 offset:784
	ds_write_b32 v24, v43 offset:912
	ds_write_b32 v24, v92 offset:1056
	ds_write_b32 v24, v76 offset:1184
	ds_write_b32 v24, v60 offset:1312
	ds_write_b32 v24, v44 offset:1440
	ds_write_b32 v24, v93 offset:1584
	ds_write_b32 v24, v77 offset:1712
	ds_write_b32 v24, v61 offset:1840
	ds_write_b32 v24, v45 offset:1968
	s_waitcnt lgkmcnt(0)
	ds_read_b128 v[8:11], v25
	ds_read_b128 v[12:15], v25 offset:16
	ds_read_b128 v[16:19], v25 offset:2112
	ds_read_b128 v[20:23], v25 offset:2128
	s_waitcnt vmcnt(6)
	v_lshlrev_b32_e32 v234, 16, v114
	v_and_b32_e32 v235, 0xffff0000, v114
	v_lshlrev_b32_e32 v236, 16, v115
	v_and_b32_e32 v237, 0xffff0000, v115
	v_lshlrev_b32_e32 v238, 16, v116
	v_and_b32_e32 v239, 0xffff0000, v116
	v_lshlrev_b32_e32 v240, 16, v117
	v_and_b32_e32 v241, 0xffff0000, v117
	s_waitcnt lgkmcnt(2)
	v_mul_f32_e32 v234, v8, v234
	v_mul_f32_e32 v235, v9, v235
	v_mul_f32_e32 v236, v10, v236
	v_mul_f32_e32 v237, v11, v237
	v_mul_f32_e32 v238, v12, v238
	v_mul_f32_e32 v239, v13, v239
	v_mul_f32_e32 v240, v14, v240
	v_mul_f32_e32 v241, v15, v241
	v_cvt_pk_bf16_f32 v28, v234, v235
	v_cvt_pk_bf16_f32 v29, v236, v237
	v_cvt_pk_bf16_f32 v30, v238, v239
	v_cvt_pk_bf16_f32 v31, v240, v241
	global_store_dwordx4 v26, v[28:31], s[50:51] sc1
	v_add_u32_e32 v27, 0x4000, v26
	v_lshlrev_b32_e32 v234, 16, v118
	v_and_b32_e32 v235, 0xffff0000, v118
	v_lshlrev_b32_e32 v236, 16, v119
	v_and_b32_e32 v237, 0xffff0000, v119
	v_lshlrev_b32_e32 v238, 16, v120
	v_and_b32_e32 v239, 0xffff0000, v120
	v_lshlrev_b32_e32 v240, 16, v121
	v_and_b32_e32 v241, 0xffff0000, v121
	s_waitcnt lgkmcnt(0)
	v_mul_f32_e32 v234, v16, v234
	v_mul_f32_e32 v235, v17, v235
	v_mul_f32_e32 v236, v18, v236
	v_mul_f32_e32 v237, v19, v237
	v_mul_f32_e32 v238, v20, v238
	v_mul_f32_e32 v239, v21, v239
	v_mul_f32_e32 v240, v22, v240
	v_mul_f32_e32 v241, v23, v241
	v_cvt_pk_bf16_f32 v242, v234, v235
	v_cvt_pk_bf16_f32 v243, v236, v237
	v_cvt_pk_bf16_f32 v244, v238, v239
	v_cvt_pk_bf16_f32 v245, v240, v241
	global_store_dwordx4 v27, v[242:245], s[50:51] sc1
	v_add_u32_e32 v26, 0x4000, v27
	ds_read_b128 v[0:3], v170 offset:96
	s_waitcnt lgkmcnt(0)
	v_mul_f32_e32 v94, v94, v0
	v_mul_f32_e32 v78, v78, v0
	v_mul_f32_e32 v62, v62, v0
	v_mul_f32_e32 v46, v46, v0
	v_mul_f32_e32 v95, v95, v1
	v_mul_f32_e32 v79, v79, v1
	v_mul_f32_e32 v63, v63, v1
	v_mul_f32_e32 v47, v47, v1
	v_mul_f32_e32 v96, v96, v2
	v_mul_f32_e32 v80, v80, v2
	v_mul_f32_e32 v64, v64, v2
	v_mul_f32_e32 v48, v48, v2
	v_mul_f32_e32 v97, v97, v3
	v_mul_f32_e32 v81, v81, v3
	v_mul_f32_e32 v65, v65, v3
	v_mul_f32_e32 v49, v49, v3
	ds_write_b32 v24, v94
	ds_write_b32 v24, v78 offset:128
	ds_write_b32 v24, v62 offset:256
	ds_write_b32 v24, v46 offset:384
	ds_write_b32 v24, v95 offset:528
	ds_write_b32 v24, v79 offset:656
	ds_write_b32 v24, v63 offset:784
	ds_write_b32 v24, v47 offset:912
	ds_write_b32 v24, v96 offset:1056
	ds_write_b32 v24, v80 offset:1184
	ds_write_b32 v24, v64 offset:1312
	ds_write_b32 v24, v48 offset:1440
	ds_write_b32 v24, v97 offset:1584
	ds_write_b32 v24, v81 offset:1712
	ds_write_b32 v24, v65 offset:1840
	ds_write_b32 v24, v49 offset:1968
	s_waitcnt lgkmcnt(0)
	ds_read_b128 v[8:11], v25
	ds_read_b128 v[12:15], v25 offset:16
	ds_read_b128 v[16:19], v25 offset:2112
	ds_read_b128 v[20:23], v25 offset:2128
	s_waitcnt vmcnt(6)
	v_lshlrev_b32_e32 v234, 16, v122
	v_and_b32_e32 v235, 0xffff0000, v122
	v_lshlrev_b32_e32 v236, 16, v123
	v_and_b32_e32 v237, 0xffff0000, v123
	v_lshlrev_b32_e32 v238, 16, v124
	v_and_b32_e32 v239, 0xffff0000, v124
	v_lshlrev_b32_e32 v240, 16, v125
	v_and_b32_e32 v241, 0xffff0000, v125
	s_waitcnt lgkmcnt(2)
	v_mul_f32_e32 v234, v8, v234
	v_mul_f32_e32 v235, v9, v235
	v_mul_f32_e32 v236, v10, v236
	v_mul_f32_e32 v237, v11, v237
	v_mul_f32_e32 v238, v12, v238
	v_mul_f32_e32 v239, v13, v239
	v_mul_f32_e32 v240, v14, v240
	v_mul_f32_e32 v241, v15, v241
	v_cvt_pk_bf16_f32 v28, v234, v235
	v_cvt_pk_bf16_f32 v29, v236, v237
	v_cvt_pk_bf16_f32 v30, v238, v239
	v_cvt_pk_bf16_f32 v31, v240, v241
	global_store_dwordx4 v26, v[28:31], s[50:51] sc1
	v_add_u32_e32 v27, 0x4000, v26
	v_lshlrev_b32_e32 v234, 16, v126
	v_and_b32_e32 v235, 0xffff0000, v126
	v_lshlrev_b32_e32 v236, 16, v127
	v_and_b32_e32 v237, 0xffff0000, v127
	v_lshlrev_b32_e32 v238, 16, v128
	v_and_b32_e32 v239, 0xffff0000, v128
	v_lshlrev_b32_e32 v240, 16, v129
	v_and_b32_e32 v241, 0xffff0000, v129
	s_waitcnt lgkmcnt(0)
	v_mul_f32_e32 v234, v16, v234
	v_mul_f32_e32 v235, v17, v235
	v_mul_f32_e32 v236, v18, v236
	v_mul_f32_e32 v237, v19, v237
	v_mul_f32_e32 v238, v20, v238
	v_mul_f32_e32 v239, v21, v239
	v_mul_f32_e32 v240, v22, v240
	v_mul_f32_e32 v241, v23, v241
	v_cvt_pk_bf16_f32 v242, v234, v235
	v_cvt_pk_bf16_f32 v243, v236, v237
	v_cvt_pk_bf16_f32 v244, v238, v239
	v_cvt_pk_bf16_f32 v245, v240, v241
	global_store_dwordx4 v27, v[242:245], s[50:51] sc1
	v_add_u32_e32 v26, 0x4000, v27
	v_readlane_b32 s8, v255, 11
	s_cmp_eq_u32 s10, s8
	s_cselect_b64 s[8:9], -1, 0
	v_mov_b32_e32 v159, v33

.LBB0_689:
	v_readlane_b32 s8, v254, 2
	s_add_i32 s14, s10, s8
	s_cmpk_gt_i32 s14, 0x3ff
	s_mov_b64 s[8:9], -1
	s_cbranch_scc1 .LBB0_688
	s_and_b32 s15, s14, 31
	s_bfe_u32 s8, s14, 0x10005
	v_lshl_add_u32 v0, s8, 2, v164
	s_lshl_b32 s9, s15, 6
	s_lshl_b32 s14, s14, 5
	v_or_b32_e32 v4, s9, v165
	v_ashrrev_i32_e32 v1, 31, v0
	s_and_b32 s16, s14, 0xfffff800
	v_lshl_add_u64 v[2:3], v[0:1], 2, s[6:7]
	v_or_b32_e32 v159, s16, v4
	global_load_dword v68, v[2:3], off
	v_or_b32_e32 v2, v159, v146
	v_mov_b64_e32 v[42:43], s[0:1]
	v_lshlrev_b32_e32 v160, 7, v0
	v_mad_i64_i32 v[4:5], s[24:25], v2, s97, v[42:43]
	v_ashrrev_i32_e32 v161, 31, v160
	v_lshl_add_u64 v[0:1], v[160:161], 1, v[4:5]
	v_lshl_add_u64 v[0:1], v[0:1], 0, v[32:33]
	global_load_dwordx4 v[34:37], v[0:1], off offset:2048 nt
	global_load_dwordx4 v[38:41], v[0:1], off offset:2080 nt
	global_load_dwordx4 v[44:47], v[0:1], off offset:2112 nt
	global_load_dwordx4 v[48:51], v[0:1], off offset:2144 nt
	global_load_dwordx4 v[52:55], v[0:1], off offset:2176 nt
	global_load_dwordx4 v[56:59], v[0:1], off offset:2208 nt
	global_load_dwordx4 v[60:63], v[0:1], off offset:2240 nt
	global_load_dwordx4 v[64:67], v[0:1], off offset:2272 nt
	v_ashrrev_i32_e32 v3, 31, v2
	v_lshlrev_b64 v[0:1], 7, v[2:3]
	v_lshl_add_u64 v[4:5], v[152:153], 0, v[0:1]
	global_load_dwordx4 v[0:3], v[4:5], off offset:48
	global_load_dwordx4 v[8:11], v[4:5], off offset:32
	global_load_dwordx4 v[12:15], v[4:5], off offset:16
	global_load_dwordx4 v[24:27], v[4:5], off
	global_load_dwordx4 v[16:19], v[148:149], off
	s_nop 0
	global_load_dwordx4 v[4:7], v[148:149], off offset:16
	global_load_dwordx4 v[20:23], v[148:149], off offset:64
	global_load_dwordx4 v[28:31], v[148:149], off offset:80
	s_sub_i32 s14, 2, s15
	s_cmp_lt_u32 s15, 2
	s_cselect_b32 s14, s14, 0
	s_or_b32 s9, s16, s9
	s_lshl_b32 s88, s8, 8
	v_mov_b32_e32 v157, v33
	s_mul_i32 s8, s14, 0x58000
	s_mov_b64 s[30:31], 0x1000
	s_sub_i32 s15, 33, s15
	s_min_u32 s15, s15, 4
	s_waitcnt vmcnt(15)
	v_lshlrev_b32_e32 v93, 16, v34
	s_waitcnt vmcnt(14)
	v_lshlrev_b32_e32 v92, 16, v38
	s_waitcnt vmcnt(13)
	v_lshlrev_b32_e32 v101, 16, v46
	v_and_b32_e32 v102, 0xffff0000, v46
	s_waitcnt vmcnt(11)
	v_lshlrev_b32_e32 v113, 16, v52
	v_and_b32_e32 v114, 0xffff0000, v52
	s_waitcnt vmcnt(10)
	v_lshlrev_b32_e32 v125, 16, v58
	v_and_b32_e32 v126, 0xffff0000, v58
	v_lshlrev_b32_e32 v127, 16, v59
	v_and_b32_e32 v128, 0xffff0000, v59
	s_waitcnt vmcnt(8)
	v_and_b32_e32 v58, 0xffff0000, v67
	v_lshlrev_b32_e32 v59, 16, v67
	v_lshlrev_b32_e32 v46, 16, v41
	v_and_b32_e32 v52, 0xffff0000, v41
	v_lshlrev_b32_e32 v41, 16, v35
	v_and_b32_e32 v67, 0xffff0000, v35
	v_and_b32_e32 v35, 0xffff0000, v34
	v_and_b32_e32 v34, 0xffff0000, v38
	v_lshlrev_b32_e32 v103, 16, v47
	v_and_b32_e32 v104, 0xffff0000, v47
	v_lshlrev_b32_e32 v115, 16, v53
	v_and_b32_e32 v116, 0xffff0000, v53
	v_lshlrev_b32_e32 v121, 16, v56
	v_and_b32_e32 v122, 0xffff0000, v56
	v_lshlrev_b32_e32 v123, 16, v57
	v_and_b32_e32 v124, 0xffff0000, v57
	v_lshlrev_b32_e32 v129, 16, v60
	v_and_b32_e32 v130, 0xffff0000, v60
	v_lshlrev_b32_e32 v131, 16, v61
	v_and_b32_e32 v132, 0xffff0000, v61
	v_and_b32_e32 v56, 0xffff0000, v66
	v_lshlrev_b32_e32 v57, 16, v66
	v_lshlrev_b32_e32 v47, 16, v37
	v_and_b32_e32 v53, 0xffff0000, v37
	v_lshlrev_b32_e32 v61, 16, v36
	v_lshlrev_b32_e32 v60, 16, v40
	v_and_b32_e32 v37, 0xffff0000, v36
	v_and_b32_e32 v36, 0xffff0000, v40
	v_lshlrev_b32_e32 v40, 16, v39
	v_and_b32_e32 v66, 0xffff0000, v39
	v_pk_mul_f32 v[94:95], v[92:93], v[92:93]
	v_pk_mul_f32 v[38:39], v[34:35], v[34:35]
	v_lshlrev_b32_e32 v69, 16, v44
	v_and_b32_e32 v98, 0xffff0000, v44
	v_lshlrev_b32_e32 v99, 16, v45
	v_and_b32_e32 v100, 0xffff0000, v45
	v_and_b32_e32 v44, 0xffff0000, v63
	v_lshlrev_b32_e32 v45, 16, v63
	s_waitcnt vmcnt(2)
	v_mov_b32_e32 v63, v4
	v_pk_mul_f32 v[88:89], v[40:41], v[40:41]
	v_add_f32_e32 v4, v95, v39
	v_pk_mul_f32 v[90:91], v[66:67], v[66:67]
	v_add_f32_e32 v4, v89, v4
	v_pk_mul_f32 v[84:85], v[60:61], v[60:61]
	v_add_f32_e32 v4, v91, v4
	v_pk_mul_f32 v[86:87], v[36:37], v[36:37]
	v_add_f32_e32 v4, v85, v4
	v_pk_mul_f32 v[80:81], v[46:47], v[46:47]
	v_add_f32_e32 v4, v87, v4
	v_pk_mul_f32 v[82:83], v[52:53], v[52:53]
	v_add_f32_e32 v4, v81, v4
	v_add_f32_e32 v4, v83, v4
	v_add_f32_e32 v4, v94, v4
	v_add_f32_e32 v4, v38, v4
	v_add_f32_e32 v4, v88, v4
	v_add_f32_e32 v4, v90, v4
	v_add_f32_e32 v4, v84, v4
	v_add_f32_e32 v4, v86, v4
	v_add_f32_e32 v4, v80, v4
	v_add_f32_e32 v4, v82, v4
	v_fmac_f32_e32 v4, v69, v69
	v_fmac_f32_e32 v4, v98, v98
	v_fmac_f32_e32 v4, v99, v99
	v_fmac_f32_e32 v4, v100, v100
	v_fmac_f32_e32 v4, v101, v101
	v_fmac_f32_e32 v4, v102, v102
	v_fmac_f32_e32 v4, v103, v103
	v_lshlrev_b32_e32 v105, 16, v48
	v_fmac_f32_e32 v4, v104, v104
	v_and_b32_e32 v106, 0xffff0000, v48
	v_fmac_f32_e32 v4, v105, v105
	v_lshlrev_b32_e32 v107, 16, v49
	v_fmac_f32_e32 v4, v106, v106
	v_and_b32_e32 v108, 0xffff0000, v49
	v_fmac_f32_e32 v4, v107, v107
	v_lshlrev_b32_e32 v109, 16, v50
	v_fmac_f32_e32 v4, v108, v108
	v_and_b32_e32 v110, 0xffff0000, v50
	v_fmac_f32_e32 v4, v109, v109
	v_lshlrev_b32_e32 v111, 16, v51
	v_fmac_f32_e32 v4, v110, v110
	v_and_b32_e32 v112, 0xffff0000, v51
	v_fmac_f32_e32 v4, v111, v111
	v_fmac_f32_e32 v4, v112, v112
	v_fmac_f32_e32 v4, v113, v113
	v_fmac_f32_e32 v4, v114, v114
	v_fmac_f32_e32 v4, v115, v115
	v_lshlrev_b32_e32 v117, 16, v54
	v_fmac_f32_e32 v4, v116, v116
	v_and_b32_e32 v118, 0xffff0000, v54
	v_fmac_f32_e32 v4, v117, v117
	v_lshlrev_b32_e32 v119, 16, v55
	v_fmac_f32_e32 v4, v118, v118
	v_and_b32_e32 v120, 0xffff0000, v55
	v_fmac_f32_e32 v4, v119, v119
	v_fmac_f32_e32 v4, v120, v120
	v_fmac_f32_e32 v4, v121, v121
	v_fmac_f32_e32 v4, v122, v122
	v_fmac_f32_e32 v4, v123, v123
	v_fmac_f32_e32 v4, v124, v124
	v_fmac_f32_e32 v4, v125, v125
	v_fmac_f32_e32 v4, v126, v126
	v_fmac_f32_e32 v4, v127, v127
	v_fmac_f32_e32 v4, v128, v128
	v_fmac_f32_e32 v4, v129, v129
	v_fmac_f32_e32 v4, v130, v130
	v_fmac_f32_e32 v4, v131, v131
	v_lshlrev_b32_e32 v133, 16, v62
	v_fmac_f32_e32 v4, v132, v132
	v_and_b32_e32 v134, 0xffff0000, v62
	v_fmac_f32_e32 v4, v133, v133
	v_pk_mul_f32 v[70:71], v[44:45], v[44:45]
	v_fmac_f32_e32 v4, v134, v134
	v_and_b32_e32 v48, 0xffff0000, v64
	v_lshlrev_b32_e32 v49, 16, v64
	v_add_f32_e32 v4, v71, v4
	v_pk_mul_f32 v[72:73], v[48:49], v[48:49]
	v_add_f32_e32 v4, v70, v4
	v_and_b32_e32 v54, 0xffff0000, v65
	v_lshlrev_b32_e32 v55, 16, v65
	v_add_f32_e32 v4, v73, v4
	v_pk_mul_f32 v[74:75], v[54:55], v[54:55]
	v_add_f32_e32 v4, v72, v4
	v_add_f32_e32 v4, v75, v4
	v_pk_mul_f32 v[76:77], v[56:57], v[56:57]
	v_add_f32_e32 v4, v74, v4
	v_add_f32_e32 v4, v77, v4
	v_pk_mul_f32 v[78:79], v[58:59], v[58:59]
	v_add_f32_e32 v4, v76, v4
	v_add_f32_e32 v4, v79, v4
	v_add_f32_e32 v4, v78, v4
	v_mov_b32_e32 v51, v6
	ds_bpermute_b32 v6, v147, v4
	s_waitcnt vmcnt(0)
	v_mov_b32_e32 v50, v30
	v_mov_b32_e32 v64, v22
	v_mov_b32_e32 v97, v16
	v_mov_b32_e32 v62, v28
	s_waitcnt lgkmcnt(0)
	v_add_f32_e32 v4, v4, v6
	v_fmamk_f32 v4, v4, 0x3c000000, v218
	v_cmp_gt_f32_e32 vcc, s18, v4
	v_mul_f32_e32 v6, 0x4b800000, v4
	v_mov_b32_e32 v96, v20
	v_cndmask_b32_e32 v4, v4, v6, vcc
	v_rsq_f32_e32 v4, v4
	v_mov_b32_e32 v65, v18
	v_mul_f32_e32 v6, 0x45800000, v4
	v_cndmask_b32_e32 v4, v4, v6, vcc
	v_mul_f32_e32 v6, 0x3e0293ee, v4
	v_mul_f32_e32 v38, v6, v104
	v_mul_f32_e32 v4, v6, v69
	v_mul_f32_e32 v22, v6, v101
	v_mul_f32_e32 v30, v6, v103
	v_cvt_pk_bf16_f32 v101, v30, v38
	v_mul_f32_e32 v38, v6, v112
	v_mul_f32_e32 v16, v6, v98
	v_cvt_pk_bf16_f32 v98, v4, v16
	v_mul_f32_e32 v4, v6, v105
	v_mul_f32_e32 v30, v6, v111
	v_cvt_pk_bf16_f32 v105, v30, v38
	v_mul_f32_e32 v38, v6, v120
	v_mul_f32_e32 v20, v6, v100
	v_mul_f32_e32 v28, v6, v102
	v_cvt_pk_bf16_f32 v100, v22, v28
	v_mul_f32_e32 v22, v6, v109
	v_mul_f32_e32 v30, v6, v119
	v_cvt_pk_bf16_f32 v109, v30, v38
	v_mul_f32_e32 v38, v6, v128
	v_mul_f32_e32 v16, v6, v106
	v_mul_f32_e32 v28, v6, v110
	v_cvt_pk_bf16_f32 v102, v4, v16
	v_mul_f32_e32 v4, v6, v113
	v_mul_f32_e32 v30, v6, v127
	v_cvt_pk_bf16_f32 v113, v30, v38
	v_mul_f32_e32 v38, v6, v44
	v_cvt_pk_bf16_f32 v104, v22, v28
	v_mul_f32_e32 v16, v6, v114
	v_mul_f32_e32 v22, v6, v117
	v_mul_f32_e32 v28, v6, v118
	v_mul_f32_e32 v30, v6, v45
	v_cvt_pk_bf16_f32 v117, v30, v38
	v_mul_f32_e32 v38, v6, v58
	v_mul_f32_e32 v18, v6, v99
	v_cvt_pk_bf16_f32 v99, v18, v20
	v_mul_f32_e32 v20, v6, v108
	v_cvt_pk_bf16_f32 v106, v4, v16
	v_cvt_pk_bf16_f32 v108, v22, v28
	v_mul_f32_e32 v4, v6, v121
	v_mul_f32_e32 v16, v6, v122
	v_mul_f32_e32 v28, v6, v126
	v_mul_f32_e32 v30, v6, v59
	v_cvt_pk_bf16_f32 v121, v30, v38
	v_pk_mul_f32 v[38:39], v[6:7], v[92:93] op_sel_hi:[0,1]
	v_mul_f32_e32 v18, v6, v107
	v_cvt_pk_bf16_f32 v103, v18, v20
	v_mul_f32_e32 v20, v6, v116
	v_mul_f32_e32 v22, v6, v125
	v_cvt_pk_bf16_f32 v110, v4, v16
	v_cvt_pk_bf16_f32 v112, v22, v28
	v_mul_f32_e32 v16, v6, v130
	v_mul_f32_e32 v28, v6, v134
	v_pk_mul_f32 v[38:39], v[96:97], v[38:39]
	v_mul_f32_e32 v18, v6, v115
	v_cvt_pk_bf16_f32 v107, v18, v20
	v_mul_f32_e32 v20, v6, v124
	v_mul_f32_e32 v4, v6, v129
	v_mul_f32_e32 v22, v6, v133
	v_cvt_pk_bf16_f32 v114, v4, v16
	v_cvt_pk_bf16_f32 v116, v22, v28
	v_mul_f32_e32 v16, v6, v48
	v_mul_f32_e32 v28, v6, v56
	v_pk_mul_f32 v[44:45], v[24:25], v[38:39] op_sel:[0,1] op_sel_hi:[1,0]
	v_pk_mul_f32 v[24:25], v[24:25], v[38:39]
	v_mul_f32_e32 v18, v6, v123
	v_cvt_pk_bf16_f32 v111, v18, v20
	v_mul_f32_e32 v20, v6, v132
	v_mul_f32_e32 v4, v6, v49
	v_mul_f32_e32 v22, v6, v57
	v_cvt_pk_bf16_f32 v118, v4, v16
	v_cvt_pk_bf16_f32 v120, v22, v28
	v_add_f32_e32 v28, v24, v25
	v_pk_mul_f32 v[24:25], v[6:7], v[34:35] op_sel_hi:[0,1]
	v_mov_b32_e32 v16, v21
	v_mul_f32_e32 v18, v6, v131
	v_cvt_pk_bf16_f32 v115, v18, v20
	v_mul_f32_e32 v20, v6, v54
	v_pk_mul_f32 v[16:17], v[16:17], v[24:25]
	v_mul_f32_e32 v18, v6, v55
	v_cvt_pk_bf16_f32 v119, v18, v20
	v_pk_mul_f32 v[20:21], v[26:27], v[16:17] op_sel:[0,1] op_sel_hi:[1,0]
	v_pk_mul_f32 v[16:17], v[26:27], v[16:17]
	v_sub_f32_e32 v24, v20, v21
	v_add_f32_e32 v25, v16, v17
	v_pk_mul_f32 v[16:17], v[6:7], v[40:41] op_sel_hi:[0,1]
	v_pk_mul_f32 v[16:17], v[64:65], v[16:17]
	v_mov_b32_e32 v18, v23
	v_pk_mul_f32 v[20:21], v[12:13], v[16:17] op_sel:[0,1] op_sel_hi:[1,0]
	v_pk_mul_f32 v[12:13], v[12:13], v[16:17]
	v_sub_f32_e32 v20, v20, v21
	v_add_f32_e32 v21, v12, v13
	v_pk_mul_f32 v[12:13], v[6:7], v[66:67] op_sel_hi:[0,1]
	v_pk_mul_f32 v[12:13], v[18:19], v[12:13]
	v_mov_b32_e32 v4, v29
	v_pk_mul_f32 v[16:17], v[14:15], v[12:13] op_sel:[0,1] op_sel_hi:[1,0]
	v_pk_mul_f32 v[12:13], v[14:15], v[12:13]
	v_sub_f32_e32 v16, v16, v17
	v_add_f32_e32 v17, v12, v13
	v_pk_mul_f32 v[12:13], v[6:7], v[60:61] op_sel_hi:[0,1]
	v_pk_mul_f32 v[12:13], v[62:63], v[12:13]
	v_sub_f32_e32 v22, v44, v45
	v_pk_mul_f32 v[14:15], v[8:9], v[12:13] op_sel:[0,1] op_sel_hi:[1,0]
	v_pk_mul_f32 v[8:9], v[8:9], v[12:13]
	v_sub_f32_e32 v14, v14, v15
	v_add_f32_e32 v12, v8, v9
	v_pk_mul_f32 v[8:9], v[6:7], v[36:37] op_sel_hi:[0,1]
	v_pk_mul_f32 v[4:5], v[4:5], v[8:9]
	v_cvt_pk_bf16_f32 v122, v22, v24
	v_cvt_pk_bf16_f32 v123, v20, v16
	v_cvt_pk_bf16_f32 v126, v28, v25
	v_cvt_pk_bf16_f32 v127, v21, v17
	s_nop 0
	v_pk_mul_f32 v[8:9], v[10:11], v[4:5] op_sel:[0,1] op_sel_hi:[1,0]
	v_pk_mul_f32 v[4:5], v[10:11], v[4:5]
	v_sub_f32_e32 v13, v8, v9
	v_add_f32_e32 v10, v4, v5
	v_pk_mul_f32 v[4:5], v[6:7], v[46:47] op_sel_hi:[0,1]
	v_pk_mul_f32 v[4:5], v[50:51], v[4:5]
	v_cvt_pk_bf16_f32 v124, v14, v13
	v_cvt_pk_bf16_f32 v128, v12, v10
	s_nop 0
	v_pk_mul_f32 v[8:9], v[0:1], v[4:5] op_sel:[0,1] op_sel_hi:[1,0]
	v_pk_mul_f32 v[0:1], v[0:1], v[4:5]
	v_sub_f32_e32 v8, v8, v9
	v_add_f32_e32 v9, v0, v1
	v_pk_mul_f32 v[0:1], v[6:7], v[52:53] op_sel_hi:[0,1]
	v_mov_b32_e32 v6, v31
	v_pk_mul_f32 v[0:1], v[6:7], v[0:1]
	s_nop 0
	v_pk_mul_f32 v[4:5], v[2:3], v[0:1] op_sel:[0,1] op_sel_hi:[1,0]
	v_pk_mul_f32 v[0:1], v[2:3], v[0:1]
	v_sub_f32_e32 v4, v4, v5
	v_add_f32_e32 v0, v0, v1
	v_cvt_pk_bf16_f32 v129, v9, v0
	v_add_u32_e32 v0, s9, v167
	v_mad_i64_i32 v[0:1], s[16:17], v0, s97, v[42:43]
	v_lshl_add_u64 v[0:1], v[0:1], 0, s[88:89]
	v_lshl_add_u64 v[0:1], v[0:1], 0, v[156:157]
	s_ashr_i32 s9, s8, 31
	v_lshl_add_u64 v[2:3], s[8:9], 1, v[0:1]
	v_cvt_pk_bf16_f32 v125, v8, v4
	v_add_co_u32_e32 v4, vcc, s93, v2
	v_lshl_add_u64 v[0:1], v[2:3], 0, s[30:31]
	s_nop 0
	v_addc_co_u32_e32 v5, vcc, 0, v3, vcc
	v_add_co_u32_e32 v2, vcc, 0x59000, v2
	global_load_dwordx4 v[130:133], v[4:5], off
	global_load_dwordx4 v[134:137], v[0:1], off offset:512
	v_addc_co_u32_e32 v3, vcc, 0, v3, vcc
	global_load_dwordx4 v[138:141], v[2:3], off
	global_load_dwordx4 v[142:145], v[2:3], off offset:512
	s_cmp_ge_i32 s14, s15
	s_waitcnt vmcnt(3)
	ds_write_b128 v171, v[130:133]
	s_waitcnt vmcnt(2)
	ds_write_b128 v171, v[134:137] offset:17408
	s_waitcnt vmcnt(1)
	ds_write_b128 v171, v[138:141] offset:8704
	s_waitcnt vmcnt(0)
	ds_write_b128 v171, v[142:145] offset:26112
	s_cbranch_scc1 .LBB0_692
	s_mov_b64 s[8:9], 0x200
	v_add_co_u32_e32 v4, vcc, 0xb0000, v0
	v_lshl_add_u64 v[2:3], v[0:1], 0, s[8:9]
	s_nop 0
	v_addc_co_u32_e32 v5, vcc, 0, v1, vcc
	v_add_co_u32_e32 v6, vcc, 0xb0000, v2
	s_nop 1
	v_addc_co_u32_e32 v7, vcc, 0, v3, vcc
	v_add_co_u32_e32 v0, vcc, 0x108000, v0
	global_load_dwordx4 v[130:133], v[4:5], off
	global_load_dwordx4 v[134:137], v[6:7], off
	v_addc_co_u32_e32 v1, vcc, 0, v1, vcc
	v_add_co_u32_e32 v2, vcc, 0x108000, v2
	s_nop 1
	v_addc_co_u32_e32 v3, vcc, 0, v3, vcc
	global_load_dwordx4 v[138:141], v[0:1], off
	global_load_dwordx4 v[142:145], v[2:3], off

.LBB0_693:
	s_add_i32 s17, s14, s16
	s_bitcmp1_b32 s16, 0
	s_cselect_b32 s8, 0x8800, 0
	s_add_i32 s23, s8, 0
	v_add_u32_e32 v0, s23, v172
	ds_read_b128 v[0:3], v0
	v_add_u32_e32 v209, s23, v174
	ds_read_b128 v[234:237], v209
	v_add_u32_e32 v209, s23, v175
	s_and_b32 s8, s17, -5
	s_cmp_eq_u32 s8, 0
	s_waitcnt lgkmcnt(1)
	v_mfma_f32_32x32x16_bf16 v[16:31], v[0:3], v[122:125], 0
	v_add_u32_e32 v0, s23, v173
	ds_read_b128 v[0:3], v0
	s_waitcnt lgkmcnt(1)
	v_mfma_f32_32x32x16_bf16 v[16:31], v[234:237], v[126:129], v[16:31]
	ds_read_b128 v[234:237], v209
	v_add_u32_e32 v209, s23, v176
	s_waitcnt lgkmcnt(1)
	v_mfma_f32_32x32x16_bf16 v[0:15], v[0:3], v[122:125], 0
	s_waitcnt lgkmcnt(0)
	v_mfma_f32_32x32x16_bf16 v[0:15], v[234:237], v[126:129], v[0:15]
	ds_read_b128 v[234:237], v209
	v_add_u32_e32 v209, s23, v177
	s_waitcnt lgkmcnt(0)
	v_mfma_f32_32x32x16_bf16 v[16:31], v[234:237], v[98:101], v[16:31]
	ds_read_b128 v[234:237], v209
	v_add_u32_e32 v209, s23, v185
	s_waitcnt lgkmcnt(0)
	v_mfma_f32_32x32x16_bf16 v[0:15], v[234:237], v[98:101], v[0:15]
	ds_read_b128 v[234:237], v209
	v_add_u32_e32 v209, s23, v190
	s_waitcnt lgkmcnt(0)
	v_mfma_f32_32x32x16_bf16 v[16:31], v[234:237], v[102:105], v[16:31]
	ds_read_b128 v[234:237], v209
	v_add_u32_e32 v209, s23, v191
	s_waitcnt lgkmcnt(0)
	v_mfma_f32_32x32x16_bf16 v[0:15], v[234:237], v[102:105], v[0:15]
	ds_read_b128 v[234:237], v209
	v_add_u32_e32 v209, s23, v192
	s_waitcnt lgkmcnt(0)
	v_mfma_f32_32x32x16_bf16 v[16:31], v[234:237], v[106:109], v[16:31]
	ds_read_b128 v[234:237], v209
	v_add_u32_e32 v209, s23, v193
	s_waitcnt lgkmcnt(0)
	v_mfma_f32_32x32x16_bf16 v[0:15], v[234:237], v[106:109], v[0:15]
	ds_read_b128 v[234:237], v209
	v_add_u32_e32 v209, s23, v194
	s_waitcnt lgkmcnt(0)
	v_mfma_f32_32x32x16_bf16 v[16:31], v[234:237], v[110:113], v[16:31]
	ds_read_b128 v[234:237], v209
	v_add_u32_e32 v209, s23, v195
	s_waitcnt lgkmcnt(0)
	v_mfma_f32_32x32x16_bf16 v[0:15], v[234:237], v[110:113], v[0:15]
	ds_read_b128 v[234:237], v209
	v_add_u32_e32 v209, s23, v196
	s_waitcnt lgkmcnt(0)
	v_mfma_f32_32x32x16_bf16 v[16:31], v[234:237], v[114:117], v[16:31]
	ds_read_b128 v[234:237], v209
	v_add_u32_e32 v209, s23, v197
	s_waitcnt lgkmcnt(0)
	v_mfma_f32_32x32x16_bf16 v[0:15], v[234:237], v[114:117], v[0:15]
	ds_read_b128 v[234:237], v209
	v_add_u32_e32 v209, s23, v198
	s_waitcnt lgkmcnt(0)
	v_mfma_f32_32x32x16_bf16 v[16:31], v[234:237], v[118:121], v[16:31]
	ds_read_b128 v[234:237], v209
	s_waitcnt lgkmcnt(0)
	v_mfma_f32_32x32x16_bf16 v[0:15], v[234:237], v[118:121], v[0:15]
	s_cselect_b32 s9, 1, 0
	s_cmp_lt_i32 s17, s15
	s_cbranch_scc1 .Lattn_nogate
	v_lshrrev_b32_e32 v138, 4, v146
	v_lshrrev_b32_e32 v140, 1, v168
	v_add_u32_e32 v138, v138, v140
	v_and_b32_e32 v140, 15, v146
	v_add_u32_e32 v138, v159, v138
	v_mul_lo_u32 v138, v138, s97
	v_lshlrev_b32_e32 v140, 4, v140
	v_lshl_add_u32 v140, v160, 1, v140
	v_add_u32_e32 v130, v138, v140
	v_add_u32_e32 v130, 0x1400, v130
	v_add_u32_e32 v131, 0xb000, v130
	v_add_u32_e32 v132, 0xb000, v131
	v_add_u32_e32 v133, 0xb000, v132
	v_add_u32_e32 v134, 0xb000, v133
	v_add_u32_e32 v135, 0xb000, v134
	v_add_u32_e32 v136, 0xb000, v135
	v_add_u32_e32 v137, 0xb000, v136
	global_load_dwordx4 v[98:101], v130, s[0:1] nt
	global_load_dwordx4 v[102:105], v131, s[0:1] nt
	global_load_dwordx4 v[106:109], v132, s[0:1] nt
	global_load_dwordx4 v[110:113], v133, s[0:1] nt
	global_load_dwordx4 v[114:117], v134, s[0:1] nt
	global_load_dwordx4 v[118:121], v135, s[0:1] nt
	global_load_dwordx4 v[122:125], v136, s[0:1] nt
	global_load_dwordx4 v[126:129], v137, s[0:1] nt
